# baseline (speedup 1.0000x reference)
; DEV int tidx() { int t = threadIdx.x; asm volatile("" : "+v"(t)); return t; }
; DEV int bidx() { int b = __builtin_amdgcn_readfirstlane(blockIdx.x); asm volatile("" : "+s"(b)); return b; }
; DEV int gdim() { int g = __builtin_amdgcn_readfirstlane(gridDim.x); asm volatile("" : "+s"(g)); return g; }
; #define ws (wsp(p))
; DEV void phase_qrope_copy(const Params& p) {
;   const u16* Q = (const u16*)(p.ws + A_Q);
;   u16* QL = (u16*)(p.ws + D_QL);
;   for (int e = bidx() * 256 + tidx(); e < 512 * 8 * 64; e += gdim() * 256) {
;     const int ts = e >> 9, h = (e >> 6) & 7, i = e & 63;
;     QL[(size_t)ts * 2560 + h * 320 + 256 + i] = Q[(size_t)(T_P + ts) * 1536 + h * 192 + 128 + i];
;   }
; }
.LBB0_401:
	v_ashrrev_i32_e32 v3, 9, v2
	v_bfe_u32 v6, v2, 6, 3
	v_add_u32_e32 v0, 0x8000, v3
	v_mul_u32_u24_e32 v8, 0xc0, v6
	v_mul_hi_i32_i24_e32 v5, 0xc00, v0
	v_mul_i32_i24_e32 v4, 0xc00, v0
	v_and_b32_e32 v7, 63, v2
	v_lshlrev_b32_e32 v0, 1, v8
	v_lshl_add_u64 v[4:5], s[50:51], 0, v[4:5]
	v_lshl_add_u64 v[4:5], v[4:5], 0, v[0:1]
	v_lshlrev_b32_e32 v0, 1, v7
	v_lshl_add_u64 v[4:5], v[4:5], 0, v[0:1]
	global_load_ushort v8, v[4:5], off
	s_mov_b32 s2, 0xc0000
	s_mov_b32 s3, 0
	v_lshl_add_u64 v[222:223], v[4:5], 0, s[2:3]
	global_load_ushort v224, v[222:223], off
	v_mul_u32_u24_e32 v4, 0x140, v6
	v_mul_hi_i32_i24_e32 v7, 0x1400, v3
	v_mul_i32_i24_e32 v6, 0x1400, v3
	v_mov_b32_e32 v5, v1
	v_lshl_add_u64 v[6:7], s[58:59], 0, v[6:7]
	v_lshlrev_b32_e32 v4, 1, v4
	v_lshl_add_u64 v[4:5], v[6:7], 0, v[4:5]
	v_lshl_add_u64 v[4:5], v[4:5], 0, v[0:1]
	s_mov_b32 s2, 0x140000
	s_nop 0
	v_lshl_add_u64 v[226:227], v[4:5], 0, s[2:3]
	s_waitcnt vmcnt(0)
	global_store_short v[4:5], v8, off
	global_store_short v[226:227], v224, off
